# attention item epilogue: gate and g_att vectors of all eight head-dim groups fetched up front instead of a dependent load pair and full vmcnt drain per group
# baseline (speedup 1.0000x reference)
.LBB0_1072:
	s_load_dwordx2 s[4:5], s[82:83], 0x40
	v_lshlrev_b32_e32 v0, 1, v208
	v_mov_b32_e32 v1, v209
	v_or_b32_e32 v10, s8, v208
	v_ashrrev_i32_e32 v11, 31, v10
	s_waitcnt lgkmcnt(0)
	s_add_u32 s76, s4, s14
	s_addc_u32 s77, s5, s15
	s_add_i32 s4, s8, 0x1000
	s_ashr_i32 s4, s4, 7
	s_ashr_i32 s5, s4, 31
	s_lshl_b64 s[4:5], s[4:5], 21
	s_add_u32 s4, s56, s4
	s_addc_u32 s5, s57, s5
	v_lshl_add_u64 v[2:3], s[4:5], 0, v[98:99]
	v_lshl_add_u64 v[8:9], v[2:3], 0, v[0:1]
	global_load_dwordx2 v[14:15], v[8:9], off
	ds_bpermute_b32 v2, v126, v135
	v_lshlrev_b64 v[0:1], 12, v[96:97]
	v_lshl_add_u64 v[0:1], s[50:51], 0, v[0:1]
	v_lshl_add_u64 v[4:5], v[0:1], 0, s[68:69]
	v_lshl_add_u64 v[0:1], v[10:11], 2, s[76:77]
	s_waitcnt lgkmcnt(0)
	v_add_f32_e32 v2, v135, v2
	ds_bpermute_b32 v3, v125, v2
	s_ashr_i32 s9, s8, 31
	s_mov_b32 s86, s46
	s_waitcnt lgkmcnt(0)
	v_add_f32_e32 v6, v2, v3
	v_div_scale_f32 v7, s[4:5], v6, v6, 1.0
	v_rcp_f32_e32 v12, v7
	v_div_scale_f32 v13, vcc, 1.0, v6, 1.0
	global_load_dwordx2 v[154:155], v[8:9], off offset:32
	global_load_dwordx2 v[156:157], v[8:9], off offset:64
	global_load_dwordx2 v[158:159], v[8:9], off offset:96
	global_load_dwordx2 v[160:161], v[8:9], off offset:128
	global_load_dwordx2 v[162:163], v[8:9], off offset:160
	global_load_dwordx2 v[164:165], v[8:9], off offset:192
	global_load_dwordx2 v[166:167], v[8:9], off offset:224
	global_load_dwordx4 v[168:171], v[0:1], off offset:64
	global_load_dwordx4 v[172:175], v[0:1], off offset:128
	global_load_dwordx4 v[176:179], v[0:1], off offset:192
	global_load_dwordx4 v[180:183], v[0:1], off offset:256
	global_load_dwordx4 v[184:187], v[0:1], off offset:320
	global_load_dwordx4 v[188:191], v[0:1], off offset:384
	global_load_dwordx4 v[192:195], v[0:1], off offset:448
	global_load_dwordx4 v[0:3], v[0:1], off
	s_waitcnt vmcnt(8)
	v_fma_f32 v32, -v7, v12, 1.0
	v_fmac_f32_e32 v12, v32, v12
	v_mul_f32_e32 v32, v13, v12
	v_fma_f32 v33, -v7, v32, v13
	v_fmac_f32_e32 v32, v33, v12
	v_fma_f32 v7, -v7, v32, v13
	v_div_fmas_f32 v7, v7, v12, v32
	s_waitcnt vmcnt(6)
	v_div_fixup_f32 v46, v7, v6, 1.0
	v_pk_mul_f32 v[12:13], v[76:77], v[46:47] op_sel_hi:[1,0]
	v_pk_mul_f32 v[6:7], v[78:79], v[46:47] op_sel_hi:[1,0]
	v_pk_mul_f32 v[40:41], v[74:75], v[46:47] op_sel_hi:[1,0]
	v_pk_mul_f32 v[42:43], v[72:73], v[46:47] op_sel_hi:[1,0]
	v_pk_mul_f32 v[44:45], v[70:71], v[46:47] op_sel_hi:[1,0]
	s_waitcnt vmcnt(5)
	v_pk_mul_f32 v[48:49], v[68:69], v[46:47] op_sel_hi:[1,0]
	v_pk_mul_f32 v[34:35], v[58:59], v[46:47] op_sel_hi:[1,0]
	v_pk_mul_f32 v[38:39], v[56:57], v[46:47] op_sel_hi:[1,0]
	v_pk_mul_f32 v[32:33], v[18:19], v[46:47] op_sel_hi:[1,0]
	v_pk_mul_f32 v[56:57], v[42:43], v[42:43]
	s_waitcnt vmcnt(4)
	v_pk_mul_f32 v[54:55], v[40:41], v[40:41]
	s_waitcnt vmcnt(3)
	v_pk_mul_f32 v[60:61], v[48:49], v[48:49]
	v_pk_mul_f32 v[58:59], v[44:45], v[44:45]
	s_waitcnt vmcnt(2)
	v_pk_mul_f32 v[64:65], v[38:39], v[38:39]
	v_pk_mul_f32 v[62:63], v[34:35], v[34:35]
	v_pk_mul_f32 v[66:67], v[32:33], v[32:33]
	v_pk_mul_f32 v[50:51], v[12:13], v[12:13]
	v_pk_mul_f32 v[52:53], v[6:7], v[6:7]
	s_waitcnt vmcnt(1)
	v_lshlrev_b32_e32 v37, 16, v14
	v_and_b32_e32 v47, 0xffff0000, v14
	v_lshlrev_b32_e32 v80, 16, v15
	v_and_b32_e32 v36, 0xffff0000, v15
	v_mul_f32_e32 v14, 0xbfb8aa3b, v37
	v_mul_f32_e32 v15, 0xbfb8aa3b, v47
	v_mul_f32_e32 v18, 0xbfb8aa3b, v80
	v_mul_f32_e32 v19, 0xbfb8aa3b, v36
	v_exp_f32_e32 v14, v14
	v_exp_f32_e32 v15, v15
	v_exp_f32_e32 v18, v18
	v_exp_f32_e32 v19, v19
	v_pk_add_f32 v[14:15], v[14:15], 1.0 op_sel_hi:[1,0]
	s_nop 0
	v_div_scale_f32 v70, s[4:5], v14, v14, v37
	v_pk_add_f32 v[68:69], v[18:19], 1.0 op_sel_hi:[1,0]
	v_div_scale_f32 v18, s[4:5], v15, v15, v47
	v_rcp_f32_e32 v74, v18
	v_div_scale_f32 v72, s[6:7], v69, v69, v36
	v_rcp_f32_e32 v75, v70
	v_rcp_f32_e32 v76, v72
	v_fma_f32 v77, -v18, v74, 1.0
	v_div_scale_f32 v19, vcc, v47, v15, v47
	v_fma_f32 v78, -v70, v75, 1.0
	v_fmac_f32_e32 v74, v77, v74
	v_div_scale_f32 v71, s[4:5], v37, v14, v37
	v_fma_f32 v79, -v72, v76, 1.0
	v_fmac_f32_e32 v75, v78, v75
	v_mul_f32_e32 v77, v19, v74
	v_div_scale_f32 v73, s[6:7], v36, v69, v36
	v_fmac_f32_e32 v76, v79, v76
	v_mul_f32_e32 v78, v71, v75
	v_fma_f32 v83, -v18, v77, v19
	v_mul_f32_e32 v79, v73, v76
	v_fma_f32 v84, -v70, v78, v71
	v_fmac_f32_e32 v77, v83, v74
	v_fma_f32 v85, -v72, v79, v73
	v_fmac_f32_e32 v78, v84, v75
	v_fma_f32 v18, -v18, v77, v19
	v_fmac_f32_e32 v79, v85, v76
	v_fma_f32 v19, -v70, v78, v71
	v_div_fmas_f32 v18, v18, v74, v77
	s_mov_b64 vcc, s[4:5]
	v_fma_f32 v72, -v72, v79, v73
	v_div_fixup_f32 v71, v18, v15, v47
	v_div_fmas_f32 v15, v19, v75, v78
	s_mov_b64 vcc, s[6:7]
	v_div_fixup_f32 v70, v15, v14, v37
	v_div_fmas_f32 v14, v72, v76, v79
	v_div_fixup_f32 v47, v14, v69, v36
	v_pk_mul_f32 v[36:37], v[16:17], v[46:47] op_sel_hi:[1,0]
	v_pk_mul_f32 v[30:31], v[30:31], v[46:47] op_sel_hi:[1,0]
	v_pk_mul_f32 v[28:29], v[28:29], v[46:47] op_sel_hi:[1,0]
	v_pk_mul_f32 v[22:23], v[22:23], v[46:47] op_sel_hi:[1,0]
	v_pk_mul_f32 v[20:21], v[20:21], v[46:47] op_sel_hi:[1,0]
	v_pk_mul_f32 v[16:17], v[26:27], v[46:47] op_sel_hi:[1,0]
	v_pk_mul_f32 v[18:19], v[24:25], v[46:47] op_sel_hi:[1,0]
	v_add_f32_e32 v46, v56, v57
	v_add_f32_e32 v46, v54, v46
	v_add_f32_e32 v46, v55, v46
	v_add_f32_e32 v46, v60, v46
	v_add_f32_e32 v46, v61, v46
	v_add_f32_e32 v46, v58, v46
	v_add_f32_e32 v46, v59, v46
	v_add_f32_e32 v46, v64, v46
	v_add_f32_e32 v46, v65, v46
	v_add_f32_e32 v46, v62, v46
	v_pk_mul_f32 v[14:15], v[36:37], v[36:37]
	v_add_f32_e32 v46, v63, v46
	v_add_f32_e32 v14, v14, v46
	v_add_f32_e32 v14, v15, v14
	v_add_f32_e32 v14, v66, v14
	v_pk_mul_f32 v[74:75], v[28:29], v[28:29]
	v_add_f32_e32 v14, v67, v14
	v_add_f32_e32 v14, v74, v14
	v_pk_mul_f32 v[72:73], v[30:31], v[30:31]
	v_add_f32_e32 v14, v75, v14
	v_add_f32_e32 v14, v72, v14
	v_pk_mul_f32 v[78:79], v[20:21], v[20:21]
	v_add_f32_e32 v14, v73, v14
	v_add_f32_e32 v14, v78, v14
	v_pk_mul_f32 v[76:77], v[22:23], v[22:23]
	v_add_f32_e32 v14, v79, v14
	v_add_f32_e32 v14, v76, v14
	v_pk_mul_f32 v[24:25], v[18:19], v[18:19]
	v_add_f32_e32 v14, v77, v14
	v_add_f32_e32 v14, v24, v14
	v_pk_mul_f32 v[26:27], v[16:17], v[16:17]
	v_add_f32_e32 v14, v25, v14
	v_add_f32_e32 v14, v26, v14
	v_add_f32_e32 v14, v27, v14
	v_add_f32_e32 v14, v50, v14
	v_add_f32_e32 v14, v51, v14
	v_add_f32_e32 v14, v52, v14
	v_add_f32_e32 v14, v53, v14
	ds_bpermute_b32 v15, v126, v14
	v_div_scale_f32 v81, s[22:23], v68, v68, v80
	v_rcp_f32_e32 v82, v81
	s_waitcnt lgkmcnt(0)
	v_add_f32_e32 v14, v14, v15
	ds_bpermute_b32 v15, v125, v14
	v_fma_f32 v24, -v81, v82, 1.0
	v_fmac_f32_e32 v82, v24, v82
	v_div_scale_f32 v24, vcc, v80, v68, v80
	s_waitcnt lgkmcnt(0)
	v_add_f32_e32 v14, v14, v15
	v_fmamk_f32 v14, v14, 0x3c000000, v231
	v_mul_f32_e32 v15, 0x4b800000, v14
	v_cmp_gt_f32_e64 s[4:5], s37, v14
	v_mul_f32_e32 v25, v24, v82
	v_fma_f32 v26, -v81, v25, v24
	v_cndmask_b32_e64 v14, v14, v15, s[4:5]
	v_rsq_f32_e32 v14, v14
	v_fmac_f32_e32 v25, v26, v82
	v_fma_f32 v24, -v81, v25, v24
	v_div_fmas_f32 v15, v24, v82, v25
	v_lshl_add_u64 v[24:25], v[10:11], 1, v[4:5]
	v_mul_f32_e32 v11, 0x45800000, v14
	v_cndmask_b32_e64 v14, v14, v11, s[4:5]
	v_pk_mul_f32 v[26:27], v[42:43], v[14:15] op_sel_hi:[1,0]
	v_div_fixup_f32 v46, v15, v68, v80
	s_waitcnt vmcnt(0)
	v_pk_mul_f32 v[0:1], v[0:1], v[26:27]
	v_pk_mul_f32 v[26:27], v[40:41], v[14:15] op_sel_hi:[1,0]
	v_pk_mul_f32 v[0:1], v[70:71], v[0:1]
	v_pk_mul_f32 v[2:3], v[2:3], v[26:27]
	v_cvt_pk_bf16_f32 v0, v0, v1
	v_pk_mul_f32 v[2:3], v[46:47], v[2:3]
	v_or_b32_e32 v40, s8, v124
	v_cvt_pk_bf16_f32 v1, v2, v3
	global_store_dwordx2 v[24:25], v[0:1], off
	v_mov_b64_e32 v[2:3], v[154:155]
	v_lshl_add_u64 v[0:1], s[8:9], 0, v[208:209]
	v_lshl_add_u64 v[0:1], v[0:1], 2, s[76:77]
	v_mov_b64_e32 v[24:25], v[168:169]
	v_mov_b64_e32 v[26:27], v[170:171]
	v_ashrrev_i32_e32 v41, 31, v40
	v_lshl_add_u64 v[40:41], v[40:41], 1, v[4:5]
	s_mov_b32 s76, s42
	v_lshlrev_b32_e32 v11, 16, v2
	v_and_b32_e32 v15, 0xffff0000, v2
	v_mul_f32_e32 v2, 0xbfb8aa3b, v11
	v_exp_f32_e32 v42, v2
	v_mul_f32_e32 v2, 0xbfb8aa3b, v15
	v_exp_f32_e32 v43, v2
	v_lshlrev_b32_e32 v50, 16, v3
	v_and_b32_e32 v51, 0xffff0000, v3
	v_pk_mul_f32 v[2:3], v[48:49], v[14:15] op_sel_hi:[1,0]
	v_pk_add_f32 v[42:43], v[42:43], 1.0 op_sel_hi:[1,0]
	v_pk_mul_f32 v[2:3], v[24:25], v[2:3]
	v_div_scale_f32 v46, s[4:5], v43, v43, v15
	v_rcp_f32_e32 v47, v46
	s_nop 0
	v_fma_f32 v24, -v46, v47, 1.0
	v_fmac_f32_e32 v47, v24, v47
	v_div_scale_f32 v24, vcc, v15, v43, v15
	v_mul_f32_e32 v25, v24, v47
	v_fma_f32 v48, -v46, v25, v24
	v_fmac_f32_e32 v25, v48, v47
	v_fma_f32 v24, -v46, v25, v24
	v_div_scale_f32 v46, s[4:5], v42, v42, v11
	v_rcp_f32_e32 v48, v46
	v_div_fmas_f32 v24, v24, v47, v25
	v_div_fixup_f32 v25, v24, v43, v15
	v_fma_f32 v15, -v46, v48, 1.0
	v_fmac_f32_e32 v48, v15, v48
	v_div_scale_f32 v15, vcc, v11, v42, v11
	v_mul_f32_e32 v24, v15, v48
	v_fma_f32 v43, -v46, v24, v15
	v_fmac_f32_e32 v24, v43, v48
	v_mul_f32_e32 v43, 0xbfb8aa3b, v50
	v_fma_f32 v15, -v46, v24, v15
	v_exp_f32_e32 v46, v43
	v_mul_f32_e32 v43, 0xbfb8aa3b, v51
	v_exp_f32_e32 v47, v43
	v_div_fmas_f32 v15, v15, v48, v24
	v_div_fixup_f32 v24, v15, v42, v11
	v_pk_mul_f32 v[2:3], v[24:25], v[2:3]
	v_pk_add_f32 v[24:25], v[46:47], 1.0 op_sel_hi:[1,0]
	v_cvt_pk_bf16_f32 v2, v2, v3
	v_div_scale_f32 v11, s[4:5], v25, v25, v51
	v_rcp_f32_e32 v15, v11
	s_nop 0
	v_fma_f32 v3, -v11, v15, 1.0
	v_pk_mul_f32 v[42:43], v[44:45], v[14:15] op_sel_hi:[1,0]
	v_fmac_f32_e32 v15, v3, v15
	v_div_scale_f32 v3, vcc, v51, v25, v51
	v_pk_mul_f32 v[26:27], v[26:27], v[42:43]
	v_mul_f32_e32 v42, v3, v15
	v_fma_f32 v43, -v11, v42, v3
	v_fmac_f32_e32 v42, v43, v15
	v_fma_f32 v3, -v11, v42, v3
	v_div_scale_f32 v11, s[4:5], v24, v24, v50
	v_rcp_f32_e32 v43, v11
	v_div_fmas_f32 v3, v3, v15, v42
	v_div_fixup_f32 v25, v3, v25, v51
	v_fma_f32 v3, -v11, v43, 1.0
	v_fmac_f32_e32 v43, v3, v43
	v_div_scale_f32 v3, vcc, v50, v24, v50
	v_mul_f32_e32 v15, v3, v43
	v_fma_f32 v42, -v11, v15, v3
	v_fmac_f32_e32 v15, v42, v43
	v_fma_f32 v3, -v11, v15, v3
	v_div_fmas_f32 v3, v3, v43, v15
	v_div_fixup_f32 v24, v3, v24, v50
	v_pk_mul_f32 v[24:25], v[24:25], v[26:27]
	v_pk_mul_f32 v[38:39], v[38:39], v[14:15] op_sel_hi:[1,0]
	v_cvt_pk_bf16_f32 v3, v24, v25
	global_store_dwordx2 v[40:41], v[2:3], off
	v_mov_b64_e32 v[2:3], v[156:157]
	s_nop 0
	v_mov_b64_e32 v[24:25], v[172:173]
	v_mov_b64_e32 v[26:27], v[174:175]
	v_or_b32_e32 v40, s8, v123
	v_ashrrev_i32_e32 v41, 31, v40
	v_lshl_add_u64 v[40:41], v[40:41], 1, v[4:5]
	v_lshlrev_b32_e32 v11, 16, v2
	v_and_b32_e32 v15, 0xffff0000, v2
	v_lshlrev_b32_e32 v42, 16, v3
	v_and_b32_e32 v43, 0xffff0000, v3
	v_pk_mul_f32 v[2:3], v[24:25], v[38:39]
	v_mul_f32_e32 v24, 0xbfb8aa3b, v11
	v_mul_f32_e32 v25, 0xbfb8aa3b, v15
	v_exp_f32_e32 v24, v24
	v_exp_f32_e32 v25, v25
	v_mul_f32_e32 v38, 0xbfb8aa3b, v42
	v_mul_f32_e32 v39, 0xbfb8aa3b, v43
	v_exp_f32_e32 v38, v38
	v_pk_add_f32 v[24:25], v[24:25], 1.0 op_sel_hi:[1,0]
	v_exp_f32_e32 v39, v39
	v_div_scale_f32 v44, s[4:5], v25, v25, v15
	v_div_scale_f32 v46, s[4:5], v24, v24, v11
	v_rcp_f32_e32 v47, v44
	v_rcp_f32_e32 v48, v46
	v_div_scale_f32 v45, vcc, v15, v25, v15
	v_fma_f32 v50, -v44, v47, 1.0
	v_fma_f32 v51, -v46, v48, 1.0
	v_fmac_f32_e32 v47, v50, v47
	v_div_scale_f32 v49, s[4:5], v11, v24, v11
	v_fmac_f32_e32 v48, v51, v48
	v_mul_f32_e32 v50, v45, v47
	v_mul_f32_e32 v51, v49, v48
	v_fma_f32 v52, -v44, v50, v45
	v_fma_f32 v53, -v46, v51, v49
	v_fmac_f32_e32 v50, v52, v47
	v_fmac_f32_e32 v51, v53, v48
	v_fma_f32 v44, -v44, v50, v45
	v_fma_f32 v45, -v46, v51, v49
	v_div_fmas_f32 v44, v44, v47, v50
	s_mov_b64 vcc, s[4:5]
	v_div_fixup_f32 v25, v44, v25, v15
	v_div_fmas_f32 v15, v45, v48, v51
	v_div_fixup_f32 v24, v15, v24, v11
	v_pk_mul_f32 v[2:3], v[24:25], v[2:3]
	v_pk_add_f32 v[24:25], v[38:39], 1.0 op_sel_hi:[1,0]
	v_cvt_pk_bf16_f32 v2, v2, v3
	v_div_scale_f32 v11, s[4:5], v25, v25, v43
	v_rcp_f32_e32 v15, v11
	s_nop 0
	v_fma_f32 v3, -v11, v15, 1.0
	v_pk_mul_f32 v[34:35], v[34:35], v[14:15] op_sel_hi:[1,0]
	v_fmac_f32_e32 v15, v3, v15
	v_div_scale_f32 v3, vcc, v43, v25, v43
	v_pk_mul_f32 v[26:27], v[26:27], v[34:35]
	v_mul_f32_e32 v34, v3, v15
	v_fma_f32 v35, -v11, v34, v3
	v_fmac_f32_e32 v34, v35, v15
	v_fma_f32 v3, -v11, v34, v3
	v_div_scale_f32 v11, s[4:5], v24, v24, v42
	v_rcp_f32_e32 v35, v11
	v_div_fmas_f32 v3, v3, v15, v34
	v_div_fixup_f32 v25, v3, v25, v43
	v_fma_f32 v3, -v11, v35, 1.0
	v_fmac_f32_e32 v35, v3, v35
	v_div_scale_f32 v3, vcc, v42, v24, v42
	v_mul_f32_e32 v15, v3, v35
	v_fma_f32 v34, -v11, v15, v3
	v_fmac_f32_e32 v15, v34, v35
	v_fma_f32 v3, -v11, v15, v3
	v_div_fmas_f32 v3, v3, v35, v15
	v_div_fixup_f32 v24, v3, v24, v42
	v_pk_mul_f32 v[24:25], v[24:25], v[26:27]
	v_pk_mul_f32 v[36:37], v[36:37], v[14:15] op_sel_hi:[1,0]
	v_cvt_pk_bf16_f32 v3, v24, v25
	global_store_dwordx2 v[40:41], v[2:3], off
	v_mov_b64_e32 v[2:3], v[158:159]
	s_nop 0
	v_mov_b64_e32 v[24:25], v[176:177]
	v_mov_b64_e32 v[26:27], v[178:179]
	v_pk_mul_f32 v[32:33], v[32:33], v[14:15] op_sel_hi:[1,0]
	v_or_b32_e32 v34, s8, v122
	v_ashrrev_i32_e32 v35, 31, v34
	v_lshl_add_u64 v[34:35], v[34:35], 1, v[4:5]
	v_lshlrev_b32_e32 v11, 16, v2
	v_and_b32_e32 v15, 0xffff0000, v2
	v_lshlrev_b32_e32 v40, 16, v3
	v_and_b32_e32 v41, 0xffff0000, v3
	v_mul_f32_e32 v2, 0xbfb8aa3b, v11
	v_mul_f32_e32 v3, 0xbfb8aa3b, v15
	v_exp_f32_e32 v2, v2
	v_exp_f32_e32 v3, v3
	v_mul_f32_e32 v38, 0xbfb8aa3b, v40
	v_mul_f32_e32 v39, 0xbfb8aa3b, v41
	v_exp_f32_e32 v38, v38
	v_exp_f32_e32 v39, v39
	v_pk_add_f32 v[2:3], v[2:3], 1.0 op_sel_hi:[1,0]
	v_pk_mul_f32 v[24:25], v[24:25], v[36:37]
	v_div_scale_f32 v36, s[4:5], v3, v3, v15
	v_pk_mul_f32 v[26:27], v[26:27], v[32:33]
	v_pk_add_f32 v[32:33], v[38:39], 1.0 op_sel_hi:[1,0]
	v_div_scale_f32 v38, s[4:5], v2, v2, v11
	v_rcp_f32_e32 v45, v36
	v_rcp_f32_e32 v46, v38
	v_div_scale_f32 v42, s[6:7], v33, v33, v41
	v_rcp_f32_e32 v47, v42
	v_fma_f32 v49, -v36, v45, 1.0
	v_div_scale_f32 v37, vcc, v15, v3, v15
	v_fma_f32 v50, -v38, v46, 1.0
	v_fmac_f32_e32 v45, v49, v45
	v_div_scale_f32 v39, s[4:5], v11, v2, v11
	v_fmac_f32_e32 v46, v50, v46
	v_mul_f32_e32 v49, v37, v45
	v_mul_f32_e32 v50, v39, v46
	v_fma_f32 v53, -v36, v49, v37
	v_div_scale_f32 v44, s[8:9], v32, v32, v40
	v_fma_f32 v51, -v42, v47, 1.0
	v_fma_f32 v54, -v38, v50, v39
	v_fmac_f32_e32 v49, v53, v45
	v_div_scale_f32 v43, s[6:7], v41, v33, v41
	v_rcp_f32_e32 v48, v44
	v_fmac_f32_e32 v47, v51, v47
	v_fmac_f32_e32 v50, v54, v46
	v_fma_f32 v36, -v36, v49, v37
	v_mul_f32_e32 v51, v43, v47
	v_fma_f32 v37, -v38, v50, v39
	v_div_fmas_f32 v36, v36, v45, v49
	s_mov_b64 vcc, s[4:5]
	v_fma_f32 v55, -v42, v51, v43
	v_div_fixup_f32 v3, v36, v3, v15
	v_div_fmas_f32 v15, v37, v46, v50
	v_fmac_f32_e32 v51, v55, v47
	v_div_fixup_f32 v2, v15, v2, v11
	v_fma_f32 v52, -v44, v48, 1.0
	v_fma_f32 v38, -v42, v51, v43
	s_mov_b64 vcc, s[6:7]
	v_pk_mul_f32 v[2:3], v[2:3], v[24:25]
	v_div_fmas_f32 v11, v38, v47, v51
	v_cvt_pk_bf16_f32 v2, v2, v3
	v_fmac_f32_e32 v48, v52, v48
	v_div_scale_f32 v3, vcc, v40, v32, v40
	v_div_fixup_f32 v25, v11, v33, v41
	v_mul_f32_e32 v11, v3, v48
	v_fma_f32 v15, -v44, v11, v3
	v_fmac_f32_e32 v11, v15, v48
	v_fma_f32 v3, -v44, v11, v3
	v_div_fmas_f32 v3, v3, v48, v11
	v_div_fixup_f32 v24, v3, v32, v40
	v_pk_mul_f32 v[24:25], v[24:25], v[26:27]
	v_pk_mul_f32 v[28:29], v[28:29], v[14:15] op_sel_hi:[1,0]
	v_cvt_pk_bf16_f32 v3, v24, v25
	global_store_dwordx2 v[34:35], v[2:3], off
	v_mov_b64_e32 v[2:3], v[160:161]
	s_nop 0
	v_mov_b64_e32 v[24:25], v[180:181]
	v_mov_b64_e32 v[26:27], v[182:183]
	v_pk_mul_f32 v[30:31], v[30:31], v[14:15] op_sel_hi:[1,0]
	v_or_b32_e32 v32, 64, v10
	v_ashrrev_i32_e32 v33, 31, v32
	v_lshl_add_u64 v[32:33], v[32:33], 1, v[4:5]
	v_lshlrev_b32_e32 v11, 16, v2
	v_and_b32_e32 v15, 0xffff0000, v2
	v_lshlrev_b32_e32 v36, 16, v3
	v_and_b32_e32 v37, 0xffff0000, v3
	v_mul_f32_e32 v2, 0xbfb8aa3b, v11
	v_mul_f32_e32 v3, 0xbfb8aa3b, v15
	v_exp_f32_e32 v2, v2
	v_exp_f32_e32 v3, v3
	v_mul_f32_e32 v34, 0xbfb8aa3b, v36
	v_mul_f32_e32 v35, 0xbfb8aa3b, v37
	v_exp_f32_e32 v34, v34
	v_exp_f32_e32 v35, v35
	v_pk_add_f32 v[2:3], v[2:3], 1.0 op_sel_hi:[1,0]
	v_pk_mul_f32 v[26:27], v[26:27], v[30:31]
	v_div_scale_f32 v30, s[4:5], v3, v3, v15
	v_pk_mul_f32 v[24:25], v[24:25], v[28:29]
	v_pk_add_f32 v[28:29], v[34:35], 1.0 op_sel_hi:[1,0]
	v_div_scale_f32 v34, s[4:5], v2, v2, v11
	v_rcp_f32_e32 v42, v30
	v_div_scale_f32 v38, s[6:7], v29, v29, v37
	v_rcp_f32_e32 v43, v34
	v_div_scale_f32 v40, s[8:9], v28, v28, v36
	v_rcp_f32_e32 v44, v38
	v_rcp_f32_e32 v45, v40
	v_fma_f32 v46, -v30, v42, 1.0
	v_div_scale_f32 v31, vcc, v15, v3, v15
	v_fma_f32 v47, -v34, v43, 1.0
	v_fmac_f32_e32 v42, v46, v42
	v_div_scale_f32 v35, s[4:5], v11, v2, v11
	v_fma_f32 v48, -v38, v44, 1.0
	v_fmac_f32_e32 v43, v47, v43
	v_mul_f32_e32 v46, v31, v42
	v_div_scale_f32 v39, s[6:7], v37, v29, v37
	v_fma_f32 v49, -v40, v45, 1.0
	v_fmac_f32_e32 v44, v48, v44
	v_mul_f32_e32 v47, v35, v43
	v_fma_f32 v50, -v30, v46, v31
	v_div_scale_f32 v41, s[8:9], v36, v28, v36
	v_fmac_f32_e32 v45, v49, v45
	v_mul_f32_e32 v48, v39, v44
	v_fma_f32 v51, -v34, v47, v35
	v_fmac_f32_e32 v46, v50, v42
	v_mul_f32_e32 v49, v41, v45
	v_fma_f32 v52, -v38, v48, v39
	v_fmac_f32_e32 v47, v51, v43
	v_fma_f32 v30, -v30, v46, v31
	v_fma_f32 v53, -v40, v49, v41
	v_fmac_f32_e32 v48, v52, v44
	v_fma_f32 v31, -v34, v47, v35
	v_div_fmas_f32 v30, v30, v42, v46
	s_mov_b64 vcc, s[4:5]
	v_fmac_f32_e32 v49, v53, v45
	v_fma_f32 v34, -v38, v48, v39
	v_div_fixup_f32 v3, v30, v3, v15
	v_div_fmas_f32 v15, v31, v43, v47
	s_mov_b64 vcc, s[6:7]
	v_fma_f32 v35, -v40, v49, v41
	v_div_fixup_f32 v2, v15, v2, v11
	v_div_fmas_f32 v11, v34, v44, v48
	s_mov_b64 vcc, s[8:9]
	v_pk_mul_f32 v[2:3], v[2:3], v[24:25]
	v_div_fixup_f32 v25, v11, v29, v37
	v_div_fmas_f32 v11, v35, v45, v49
	v_div_fixup_f32 v24, v11, v28, v36
	v_pk_mul_f32 v[24:25], v[24:25], v[26:27]
	v_cvt_pk_bf16_f32 v2, v2, v3
	v_cvt_pk_bf16_f32 v3, v24, v25
	global_store_dwordx2 v[32:33], v[2:3], off
	v_mov_b64_e32 v[2:3], v[162:163]
	s_nop 0
	v_mov_b64_e32 v[24:25], v[184:185]
	v_mov_b64_e32 v[26:27], v[186:187]
	v_pk_mul_f32 v[20:21], v[20:21], v[14:15] op_sel_hi:[1,0]
	v_pk_mul_f32 v[22:23], v[22:23], v[14:15] op_sel_hi:[1,0]
	v_or_b32_e32 v28, 0x50, v10
	v_ashrrev_i32_e32 v29, 31, v28
	v_lshl_add_u64 v[28:29], v[28:29], 1, v[4:5]
	v_lshlrev_b32_e32 v11, 16, v2
	v_and_b32_e32 v15, 0xffff0000, v2
	v_lshlrev_b32_e32 v32, 16, v3
	v_and_b32_e32 v33, 0xffff0000, v3
	v_mul_f32_e32 v2, 0xbfb8aa3b, v11
	v_mul_f32_e32 v3, 0xbfb8aa3b, v15
	v_exp_f32_e32 v2, v2
	v_exp_f32_e32 v3, v3
	v_mul_f32_e32 v30, 0xbfb8aa3b, v32
	v_mul_f32_e32 v31, 0xbfb8aa3b, v33
	v_exp_f32_e32 v30, v30
	v_exp_f32_e32 v31, v31
	v_pk_add_f32 v[2:3], v[2:3], 1.0 op_sel_hi:[1,0]
	v_pk_mul_f32 v[22:23], v[26:27], v[22:23]
	v_div_scale_f32 v26, s[4:5], v3, v3, v15
	v_pk_mul_f32 v[20:21], v[24:25], v[20:21]
	v_pk_add_f32 v[24:25], v[30:31], 1.0 op_sel_hi:[1,0]
	v_div_scale_f32 v30, s[4:5], v2, v2, v11
	v_rcp_f32_e32 v38, v26
	v_div_scale_f32 v34, s[6:7], v25, v25, v33
	v_rcp_f32_e32 v39, v30
	v_div_scale_f32 v36, s[8:9], v24, v24, v32
	v_rcp_f32_e32 v40, v34
	v_rcp_f32_e32 v41, v36
	v_fma_f32 v42, -v26, v38, 1.0
	v_div_scale_f32 v27, vcc, v15, v3, v15
	v_fma_f32 v43, -v30, v39, 1.0
	v_fmac_f32_e32 v38, v42, v38
	v_div_scale_f32 v31, s[4:5], v11, v2, v11
	v_fma_f32 v44, -v34, v40, 1.0
	v_fmac_f32_e32 v39, v43, v39
	v_mul_f32_e32 v42, v27, v38
	v_div_scale_f32 v35, s[6:7], v33, v25, v33
	v_fma_f32 v45, -v36, v41, 1.0
	v_fmac_f32_e32 v40, v44, v40
	v_mul_f32_e32 v43, v31, v39
	v_fma_f32 v46, -v26, v42, v27
	v_div_scale_f32 v37, s[8:9], v32, v24, v32
	v_fmac_f32_e32 v41, v45, v41
	v_mul_f32_e32 v44, v35, v40
	v_fma_f32 v47, -v30, v43, v31
	v_fmac_f32_e32 v42, v46, v38
	v_mul_f32_e32 v45, v37, v41
	v_fma_f32 v48, -v34, v44, v35
	v_fmac_f32_e32 v43, v47, v39
	v_fma_f32 v26, -v26, v42, v27
	v_fma_f32 v49, -v36, v45, v37
	v_fmac_f32_e32 v44, v48, v40
	v_fma_f32 v27, -v30, v43, v31
	v_div_fmas_f32 v26, v26, v38, v42
	s_mov_b64 vcc, s[4:5]
	v_fmac_f32_e32 v45, v49, v41
	v_fma_f32 v30, -v34, v44, v35
	v_div_fixup_f32 v3, v26, v3, v15
	v_div_fmas_f32 v15, v27, v39, v43
	s_mov_b64 vcc, s[6:7]
	v_fma_f32 v31, -v36, v45, v37
	v_div_fixup_f32 v2, v15, v2, v11
	v_div_fmas_f32 v11, v30, v40, v44
	s_mov_b64 vcc, s[8:9]
	v_pk_mul_f32 v[2:3], v[2:3], v[20:21]
	v_div_fixup_f32 v21, v11, v25, v33
	v_div_fmas_f32 v11, v31, v41, v45
	v_div_fixup_f32 v20, v11, v24, v32
	v_pk_mul_f32 v[20:21], v[20:21], v[22:23]
	v_cvt_pk_bf16_f32 v2, v2, v3
	v_cvt_pk_bf16_f32 v3, v20, v21
	global_store_dwordx2 v[28:29], v[2:3], off
	v_mov_b64_e32 v[2:3], v[164:165]
	s_nop 0
	v_mov_b64_e32 v[20:21], v[188:189]
	v_mov_b64_e32 v[22:23], v[190:191]
	v_pk_mul_f32 v[18:19], v[18:19], v[14:15] op_sel_hi:[1,0]
	v_pk_mul_f32 v[16:17], v[16:17], v[14:15] op_sel_hi:[1,0]
	v_or_b32_e32 v24, 0x60, v10
	v_ashrrev_i32_e32 v25, 31, v24
	v_lshl_add_u64 v[24:25], v[24:25], 1, v[4:5]
	v_or_b32_e32 v10, 0x70, v10
	v_lshlrev_b32_e32 v11, 16, v2
	v_and_b32_e32 v15, 0xffff0000, v2
	v_lshlrev_b32_e32 v28, 16, v3
	v_and_b32_e32 v29, 0xffff0000, v3
	v_mul_f32_e32 v2, 0xbfb8aa3b, v11
	v_mul_f32_e32 v3, 0xbfb8aa3b, v15
	v_exp_f32_e32 v2, v2
	v_exp_f32_e32 v3, v3
	v_mul_f32_e32 v26, 0xbfb8aa3b, v28
	v_mul_f32_e32 v27, 0xbfb8aa3b, v29
	v_exp_f32_e32 v26, v26
	v_exp_f32_e32 v27, v27
	v_pk_add_f32 v[2:3], v[2:3], 1.0 op_sel_hi:[1,0]
	v_pk_mul_f32 v[16:17], v[22:23], v[16:17]
	v_div_scale_f32 v22, s[4:5], v3, v3, v15
	v_pk_mul_f32 v[18:19], v[20:21], v[18:19]
	v_pk_add_f32 v[20:21], v[26:27], 1.0 op_sel_hi:[1,0]
	v_div_scale_f32 v26, s[4:5], v2, v2, v11
	v_rcp_f32_e32 v34, v22
	v_div_scale_f32 v30, s[6:7], v21, v21, v29
	v_rcp_f32_e32 v35, v26
	v_div_scale_f32 v32, s[8:9], v20, v20, v28
	v_rcp_f32_e32 v36, v30
	v_rcp_f32_e32 v37, v32
	v_fma_f32 v38, -v22, v34, 1.0
	v_div_scale_f32 v23, vcc, v15, v3, v15
	v_fma_f32 v39, -v26, v35, 1.0
	v_fmac_f32_e32 v34, v38, v34
	v_div_scale_f32 v27, s[4:5], v11, v2, v11
	v_fma_f32 v40, -v30, v36, 1.0
	v_fmac_f32_e32 v35, v39, v35
	v_mul_f32_e32 v38, v23, v34
	v_div_scale_f32 v31, s[6:7], v29, v21, v29
	v_fma_f32 v41, -v32, v37, 1.0
	v_fmac_f32_e32 v36, v40, v36
	v_mul_f32_e32 v39, v27, v35
	v_fma_f32 v42, -v22, v38, v23
	v_div_scale_f32 v33, s[8:9], v28, v20, v28
	v_fmac_f32_e32 v37, v41, v37
	v_mul_f32_e32 v40, v31, v36
	v_fma_f32 v43, -v26, v39, v27
	v_fmac_f32_e32 v38, v42, v34
	v_mul_f32_e32 v41, v33, v37
	v_fma_f32 v44, -v30, v40, v31
	v_fmac_f32_e32 v39, v43, v35
	v_fma_f32 v22, -v22, v38, v23
	v_fma_f32 v45, -v32, v41, v33
	v_fmac_f32_e32 v40, v44, v36
	v_fma_f32 v23, -v26, v39, v27
	v_div_fmas_f32 v22, v22, v34, v38
	s_mov_b64 vcc, s[4:5]
	v_fmac_f32_e32 v41, v45, v37
	v_fma_f32 v26, -v30, v40, v31
	v_div_fixup_f32 v3, v22, v3, v15
	v_div_fmas_f32 v15, v23, v35, v39
	s_mov_b64 vcc, s[6:7]
	v_fma_f32 v27, -v32, v41, v33
	v_div_fixup_f32 v2, v15, v2, v11
	v_div_fmas_f32 v11, v26, v36, v40
	s_mov_b64 vcc, s[8:9]
	v_pk_mul_f32 v[2:3], v[2:3], v[18:19]
	v_div_fixup_f32 v19, v11, v21, v29
	v_div_fmas_f32 v11, v27, v37, v41
	v_div_fixup_f32 v18, v11, v20, v28
	v_pk_mul_f32 v[16:17], v[18:19], v[16:17]
	v_cvt_pk_bf16_f32 v2, v2, v3
	v_cvt_pk_bf16_f32 v3, v16, v17
	global_store_dwordx2 v[24:25], v[2:3], off
	v_mov_b64_e32 v[8:9], v[166:167]
	s_nop 0
	v_mov_b64_e32 v[0:1], v[192:193]
	v_mov_b64_e32 v[2:3], v[194:195]
	v_pk_mul_f32 v[12:13], v[12:13], v[14:15] op_sel_hi:[1,0]
	v_pk_mul_f32 v[6:7], v[6:7], v[14:15] op_sel_hi:[1,0]
	v_ashrrev_i32_e32 v11, 31, v10
	v_lshlrev_b32_e32 v16, 16, v8
	v_and_b32_e32 v17, 0xffff0000, v8
	v_lshlrev_b32_e32 v18, 16, v9
	v_and_b32_e32 v19, 0xffff0000, v9
	v_mul_f32_e32 v8, 0xbfb8aa3b, v16
	v_mul_f32_e32 v9, 0xbfb8aa3b, v17
	v_exp_f32_e32 v8, v8
	v_exp_f32_e32 v9, v9
	v_mul_f32_e32 v14, 0xbfb8aa3b, v18
	v_mul_f32_e32 v15, 0xbfb8aa3b, v19
	v_exp_f32_e32 v14, v14
	v_exp_f32_e32 v15, v15
	v_pk_mul_f32 v[2:3], v[2:3], v[6:7]
	v_pk_add_f32 v[6:7], v[8:9], 1.0 op_sel_hi:[1,0]
	v_pk_mul_f32 v[0:1], v[0:1], v[12:13]
	v_div_scale_f32 v12, s[4:5], v7, v7, v17
	v_pk_add_f32 v[8:9], v[14:15], 1.0 op_sel_hi:[1,0]
	v_div_scale_f32 v14, s[4:5], v6, v6, v16
	v_rcp_f32_e32 v24, v12
	v_div_scale_f32 v20, s[6:7], v9, v9, v19
	v_rcp_f32_e32 v25, v14
	v_div_scale_f32 v22, s[8:9], v8, v8, v18
	v_rcp_f32_e32 v26, v20
	v_rcp_f32_e32 v27, v22
	v_fma_f32 v28, -v12, v24, 1.0
	v_div_scale_f32 v13, vcc, v17, v7, v17
	v_fma_f32 v29, -v14, v25, 1.0
	v_fmac_f32_e32 v24, v28, v24
	v_div_scale_f32 v15, s[4:5], v16, v6, v16
	v_fma_f32 v30, -v20, v26, 1.0
	v_fmac_f32_e32 v25, v29, v25
	v_mul_f32_e32 v28, v13, v24
	v_div_scale_f32 v21, s[6:7], v19, v9, v19
	v_fma_f32 v31, -v22, v27, 1.0
	v_fmac_f32_e32 v26, v30, v26
	v_mul_f32_e32 v29, v15, v25
	v_fma_f32 v32, -v12, v28, v13
	v_div_scale_f32 v23, s[8:9], v18, v8, v18
	v_fmac_f32_e32 v27, v31, v27
	v_mul_f32_e32 v30, v21, v26
	v_fma_f32 v33, -v14, v29, v15
	v_fmac_f32_e32 v28, v32, v24
	v_mul_f32_e32 v31, v23, v27
	v_fma_f32 v34, -v20, v30, v21
	v_fmac_f32_e32 v29, v33, v25
	v_fma_f32 v12, -v12, v28, v13
	v_fma_f32 v35, -v22, v31, v23
	v_fmac_f32_e32 v30, v34, v26
	v_fma_f32 v13, -v14, v29, v15
	v_div_fmas_f32 v12, v12, v24, v28
	s_mov_b64 vcc, s[4:5]
	v_fmac_f32_e32 v31, v35, v27
	v_fma_f32 v14, -v20, v30, v21
	v_div_fixup_f32 v7, v12, v7, v17
	v_div_fmas_f32 v12, v13, v25, v29
	s_mov_b64 vcc, s[6:7]
	v_fma_f32 v15, -v22, v31, v23
	v_div_fixup_f32 v6, v12, v6, v16
	v_div_fmas_f32 v12, v14, v26, v30
	s_mov_b64 vcc, s[8:9]
	v_pk_mul_f32 v[0:1], v[6:7], v[0:1]
	v_div_fmas_f32 v6, v15, v27, v31
	v_div_fixup_f32 v7, v12, v9, v19
	v_div_fixup_f32 v6, v6, v8, v18
	v_pk_mul_f32 v[2:3], v[6:7], v[2:3]
	v_cvt_pk_bf16_f32 v0, v0, v1
	v_cvt_pk_bf16_f32 v1, v2, v3
	v_lshl_add_u64 v[2:3], v[10:11], 1, v[4:5]
	global_store_dwordx2 v[2:3], v[0:1], off

.LBB0_1100:
	s_load_dwordx2 s[4:5], s[82:83], 0x40
	v_lshlrev_b32_e32 v0, 1, v208
	v_mov_b32_e32 v1, v209
	v_or_b32_e32 v12, s8, v208
	v_ashrrev_i32_e32 v13, 31, v12
	s_waitcnt lgkmcnt(0)
	s_add_u32 s76, s4, s14
	s_addc_u32 s77, s5, s15
	s_add_i32 s4, s8, 0x1000
	s_ashr_i32 s4, s4, 7
	s_ashr_i32 s5, s4, 31
	s_lshl_b64 s[4:5], s[4:5], 21
	s_add_u32 s4, s80, s4
	s_addc_u32 s5, s81, s5
	v_lshl_add_u64 v[2:3], s[4:5], 0, v[98:99]
	v_lshl_add_u64 v[10:11], v[2:3], 0, v[0:1]
	global_load_dwordx2 v[14:15], v[10:11], off
	ds_bpermute_b32 v2, v126, v135
	v_lshlrev_b64 v[0:1], 12, v[96:97]
	v_lshl_add_u64 v[0:1], s[56:57], 0, v[0:1]
	v_lshl_add_u64 v[4:5], v[0:1], 0, s[68:69]
	v_lshl_add_u64 v[0:1], v[12:13], 2, s[76:77]
	s_waitcnt lgkmcnt(0)
	v_add_f32_e32 v2, v135, v2
	ds_bpermute_b32 v3, v125, v2
	s_ashr_i32 s9, s8, 31
	s_mov_b32 s86, s46
	s_waitcnt lgkmcnt(0)
	v_add_f32_e32 v6, v2, v3
	v_div_scale_f32 v7, s[4:5], v6, v6, 1.0
	v_rcp_f32_e32 v8, v7
	v_div_scale_f32 v9, vcc, 1.0, v6, 1.0
	global_load_dwordx2 v[154:155], v[10:11], off offset:32
	global_load_dwordx2 v[156:157], v[10:11], off offset:64
	global_load_dwordx2 v[158:159], v[10:11], off offset:96
	global_load_dwordx2 v[160:161], v[10:11], off offset:128
	global_load_dwordx2 v[162:163], v[10:11], off offset:160
	global_load_dwordx2 v[164:165], v[10:11], off offset:192
	global_load_dwordx2 v[166:167], v[10:11], off offset:224
	global_load_dwordx4 v[168:171], v[0:1], off offset:64
	global_load_dwordx4 v[172:175], v[0:1], off offset:128
	global_load_dwordx4 v[176:179], v[0:1], off offset:192
	global_load_dwordx4 v[180:183], v[0:1], off offset:256
	global_load_dwordx4 v[184:187], v[0:1], off offset:320
	global_load_dwordx4 v[188:191], v[0:1], off offset:384
	global_load_dwordx4 v[192:195], v[0:1], off offset:448
	global_load_dwordx4 v[0:3], v[0:1], off
	s_waitcnt vmcnt(8)
	v_fma_f32 v32, -v7, v8, 1.0
	v_fmac_f32_e32 v8, v32, v8
	v_mul_f32_e32 v32, v9, v8
	v_fma_f32 v33, -v7, v32, v9
	v_fmac_f32_e32 v32, v33, v8
	v_fma_f32 v7, -v7, v32, v9
	v_div_fmas_f32 v7, v7, v8, v32
	s_waitcnt vmcnt(6)
	v_div_fixup_f32 v46, v7, v6, 1.0
	v_pk_mul_f32 v[6:7], v[76:77], v[46:47] op_sel_hi:[1,0]
	v_pk_mul_f32 v[8:9], v[78:79], v[46:47] op_sel_hi:[1,0]
	v_pk_mul_f32 v[40:41], v[74:75], v[46:47] op_sel_hi:[1,0]
	v_pk_mul_f32 v[42:43], v[72:73], v[46:47] op_sel_hi:[1,0]
	v_pk_mul_f32 v[44:45], v[70:71], v[46:47] op_sel_hi:[1,0]
	s_waitcnt vmcnt(5)
	v_pk_mul_f32 v[48:49], v[68:69], v[46:47] op_sel_hi:[1,0]
	v_pk_mul_f32 v[34:35], v[58:59], v[46:47] op_sel_hi:[1,0]
	v_pk_mul_f32 v[38:39], v[56:57], v[46:47] op_sel_hi:[1,0]
	v_pk_mul_f32 v[32:33], v[18:19], v[46:47] op_sel_hi:[1,0]
	v_pk_mul_f32 v[56:57], v[42:43], v[42:43]
	s_waitcnt vmcnt(4)
	v_pk_mul_f32 v[54:55], v[40:41], v[40:41]
	s_waitcnt vmcnt(3)
	v_pk_mul_f32 v[60:61], v[48:49], v[48:49]
	v_pk_mul_f32 v[58:59], v[44:45], v[44:45]
	s_waitcnt vmcnt(2)
	v_pk_mul_f32 v[64:65], v[38:39], v[38:39]
	v_pk_mul_f32 v[62:63], v[34:35], v[34:35]
	v_pk_mul_f32 v[66:67], v[32:33], v[32:33]
	v_pk_mul_f32 v[50:51], v[6:7], v[6:7]
	v_pk_mul_f32 v[52:53], v[8:9], v[8:9]
	s_waitcnt vmcnt(1)
	v_lshlrev_b32_e32 v37, 16, v14
	v_and_b32_e32 v47, 0xffff0000, v14
	v_lshlrev_b32_e32 v80, 16, v15
	v_and_b32_e32 v36, 0xffff0000, v15
	v_mul_f32_e32 v14, 0xbfb8aa3b, v37
	v_mul_f32_e32 v15, 0xbfb8aa3b, v47
	v_mul_f32_e32 v18, 0xbfb8aa3b, v80
	v_mul_f32_e32 v19, 0xbfb8aa3b, v36
	v_exp_f32_e32 v14, v14
	v_exp_f32_e32 v15, v15
	v_exp_f32_e32 v18, v18
	v_exp_f32_e32 v19, v19
	v_pk_add_f32 v[14:15], v[14:15], 1.0 op_sel_hi:[1,0]
	s_nop 0
	v_div_scale_f32 v70, s[4:5], v14, v14, v37
	v_pk_add_f32 v[68:69], v[18:19], 1.0 op_sel_hi:[1,0]
	v_div_scale_f32 v18, s[4:5], v15, v15, v47
	v_rcp_f32_e32 v74, v18
	v_div_scale_f32 v72, s[6:7], v69, v69, v36
	v_rcp_f32_e32 v75, v70
	v_rcp_f32_e32 v76, v72
	v_fma_f32 v77, -v18, v74, 1.0
	v_div_scale_f32 v19, vcc, v47, v15, v47
	v_fma_f32 v78, -v70, v75, 1.0
	v_fmac_f32_e32 v74, v77, v74
	v_div_scale_f32 v71, s[4:5], v37, v14, v37
	v_fma_f32 v79, -v72, v76, 1.0
	v_fmac_f32_e32 v75, v78, v75
	v_mul_f32_e32 v77, v19, v74
	v_div_scale_f32 v73, s[6:7], v36, v69, v36
	v_fmac_f32_e32 v76, v79, v76
	v_mul_f32_e32 v78, v71, v75
	v_fma_f32 v83, -v18, v77, v19
	v_mul_f32_e32 v79, v73, v76
	v_fma_f32 v84, -v70, v78, v71
	v_fmac_f32_e32 v77, v83, v74
	v_fma_f32 v85, -v72, v79, v73
	v_fmac_f32_e32 v78, v84, v75
	v_fma_f32 v18, -v18, v77, v19
	v_fmac_f32_e32 v79, v85, v76
	v_fma_f32 v19, -v70, v78, v71
	v_div_fmas_f32 v18, v18, v74, v77
	s_mov_b64 vcc, s[4:5]
	v_fma_f32 v72, -v72, v79, v73
	v_div_fixup_f32 v71, v18, v15, v47
	v_div_fmas_f32 v15, v19, v75, v78
	s_mov_b64 vcc, s[6:7]
	v_div_fixup_f32 v70, v15, v14, v37
	v_div_fmas_f32 v14, v72, v76, v79
	v_div_fixup_f32 v47, v14, v69, v36
	v_pk_mul_f32 v[36:37], v[16:17], v[46:47] op_sel_hi:[1,0]
	v_pk_mul_f32 v[30:31], v[30:31], v[46:47] op_sel_hi:[1,0]
	v_pk_mul_f32 v[28:29], v[28:29], v[46:47] op_sel_hi:[1,0]
	v_pk_mul_f32 v[22:23], v[22:23], v[46:47] op_sel_hi:[1,0]
	v_pk_mul_f32 v[20:21], v[20:21], v[46:47] op_sel_hi:[1,0]
	v_pk_mul_f32 v[16:17], v[26:27], v[46:47] op_sel_hi:[1,0]
	v_pk_mul_f32 v[18:19], v[24:25], v[46:47] op_sel_hi:[1,0]
	v_add_f32_e32 v46, v56, v57
	v_add_f32_e32 v46, v54, v46
	v_add_f32_e32 v46, v55, v46
	v_add_f32_e32 v46, v60, v46
	v_add_f32_e32 v46, v61, v46
	v_add_f32_e32 v46, v58, v46
	v_add_f32_e32 v46, v59, v46
	v_add_f32_e32 v46, v64, v46
	v_add_f32_e32 v46, v65, v46
	v_add_f32_e32 v46, v62, v46
	v_pk_mul_f32 v[14:15], v[36:37], v[36:37]
	v_add_f32_e32 v46, v63, v46
	v_add_f32_e32 v14, v14, v46
	v_add_f32_e32 v14, v15, v14
	v_add_f32_e32 v14, v66, v14
	v_pk_mul_f32 v[74:75], v[28:29], v[28:29]
	v_add_f32_e32 v14, v67, v14
	v_add_f32_e32 v14, v74, v14
	v_pk_mul_f32 v[72:73], v[30:31], v[30:31]
	v_add_f32_e32 v14, v75, v14
	v_add_f32_e32 v14, v72, v14
	v_pk_mul_f32 v[78:79], v[20:21], v[20:21]
	v_add_f32_e32 v14, v73, v14
	v_add_f32_e32 v14, v78, v14
	v_pk_mul_f32 v[76:77], v[22:23], v[22:23]
	v_add_f32_e32 v14, v79, v14
	v_add_f32_e32 v14, v76, v14
	v_pk_mul_f32 v[24:25], v[18:19], v[18:19]
	v_add_f32_e32 v14, v77, v14
	v_add_f32_e32 v14, v24, v14
	v_pk_mul_f32 v[26:27], v[16:17], v[16:17]
	v_add_f32_e32 v14, v25, v14
	v_add_f32_e32 v14, v26, v14
	v_add_f32_e32 v14, v27, v14
	v_add_f32_e32 v14, v50, v14
	v_add_f32_e32 v14, v51, v14
	v_add_f32_e32 v14, v52, v14
	v_add_f32_e32 v14, v53, v14
	ds_bpermute_b32 v15, v126, v14
	v_div_scale_f32 v81, s[22:23], v68, v68, v80
	v_rcp_f32_e32 v82, v81
	s_waitcnt lgkmcnt(0)
	v_add_f32_e32 v14, v14, v15
	ds_bpermute_b32 v15, v125, v14
	v_fma_f32 v24, -v81, v82, 1.0
	v_fmac_f32_e32 v82, v24, v82
	v_div_scale_f32 v24, vcc, v80, v68, v80
	s_waitcnt lgkmcnt(0)
	v_add_f32_e32 v14, v14, v15
	v_fmamk_f32 v14, v14, 0x3c000000, v231
	v_mul_f32_e32 v15, 0x4b800000, v14
	v_cmp_gt_f32_e64 s[4:5], s37, v14
	v_mul_f32_e32 v25, v24, v82
	v_fma_f32 v26, -v81, v25, v24
	v_cndmask_b32_e64 v14, v14, v15, s[4:5]
	v_rsq_f32_e32 v14, v14
	v_fmac_f32_e32 v25, v26, v82
	v_fma_f32 v24, -v81, v25, v24
	v_div_fmas_f32 v15, v24, v82, v25
	v_lshl_add_u64 v[24:25], v[12:13], 1, v[4:5]
	v_mul_f32_e32 v13, 0x45800000, v14
	v_cndmask_b32_e64 v14, v14, v13, s[4:5]
	v_pk_mul_f32 v[26:27], v[42:43], v[14:15] op_sel_hi:[1,0]
	v_div_fixup_f32 v46, v15, v68, v80
	s_waitcnt vmcnt(0)
	v_pk_mul_f32 v[0:1], v[0:1], v[26:27]
	v_pk_mul_f32 v[26:27], v[40:41], v[14:15] op_sel_hi:[1,0]
	v_pk_mul_f32 v[0:1], v[70:71], v[0:1]
	v_pk_mul_f32 v[2:3], v[2:3], v[26:27]
	v_cvt_pk_bf16_f32 v0, v0, v1
	v_pk_mul_f32 v[2:3], v[46:47], v[2:3]
	v_or_b32_e32 v40, s8, v124
	v_cvt_pk_bf16_f32 v1, v2, v3
	global_store_dwordx2 v[24:25], v[0:1], off
	v_mov_b64_e32 v[2:3], v[154:155]
	v_lshl_add_u64 v[0:1], s[8:9], 0, v[208:209]
	v_lshl_add_u64 v[0:1], v[0:1], 2, s[76:77]
	v_mov_b64_e32 v[24:25], v[168:169]
	v_mov_b64_e32 v[26:27], v[170:171]
	v_ashrrev_i32_e32 v41, 31, v40
	v_lshl_add_u64 v[40:41], v[40:41], 1, v[4:5]
	s_mov_b32 s76, s43
	v_lshlrev_b32_e32 v13, 16, v2
	v_and_b32_e32 v15, 0xffff0000, v2
	v_mul_f32_e32 v2, 0xbfb8aa3b, v13
	v_exp_f32_e32 v42, v2
	v_mul_f32_e32 v2, 0xbfb8aa3b, v15
	v_exp_f32_e32 v43, v2
	v_lshlrev_b32_e32 v50, 16, v3
	v_and_b32_e32 v51, 0xffff0000, v3
	v_pk_mul_f32 v[2:3], v[48:49], v[14:15] op_sel_hi:[1,0]
	v_pk_add_f32 v[42:43], v[42:43], 1.0 op_sel_hi:[1,0]
	v_pk_mul_f32 v[2:3], v[24:25], v[2:3]
	v_div_scale_f32 v46, s[4:5], v43, v43, v15
	v_rcp_f32_e32 v47, v46
	s_nop 0
	v_fma_f32 v24, -v46, v47, 1.0
	v_fmac_f32_e32 v47, v24, v47
	v_div_scale_f32 v24, vcc, v15, v43, v15
	v_mul_f32_e32 v25, v24, v47
	v_fma_f32 v48, -v46, v25, v24
	v_fmac_f32_e32 v25, v48, v47
	v_fma_f32 v24, -v46, v25, v24
	v_div_scale_f32 v46, s[4:5], v42, v42, v13
	v_rcp_f32_e32 v48, v46
	v_div_fmas_f32 v24, v24, v47, v25
	v_div_fixup_f32 v25, v24, v43, v15
	v_fma_f32 v15, -v46, v48, 1.0
	v_fmac_f32_e32 v48, v15, v48
	v_div_scale_f32 v15, vcc, v13, v42, v13
	v_mul_f32_e32 v24, v15, v48
	v_fma_f32 v43, -v46, v24, v15
	v_fmac_f32_e32 v24, v43, v48
	v_mul_f32_e32 v43, 0xbfb8aa3b, v50
	v_fma_f32 v15, -v46, v24, v15
	v_exp_f32_e32 v46, v43
	v_mul_f32_e32 v43, 0xbfb8aa3b, v51
	v_exp_f32_e32 v47, v43
	v_div_fmas_f32 v15, v15, v48, v24
	v_div_fixup_f32 v24, v15, v42, v13
	v_pk_mul_f32 v[2:3], v[24:25], v[2:3]
	v_pk_add_f32 v[24:25], v[46:47], 1.0 op_sel_hi:[1,0]
	v_cvt_pk_bf16_f32 v2, v2, v3
	v_div_scale_f32 v13, s[4:5], v25, v25, v51
	v_rcp_f32_e32 v15, v13
	s_nop 0
	v_fma_f32 v3, -v13, v15, 1.0
	v_pk_mul_f32 v[42:43], v[44:45], v[14:15] op_sel_hi:[1,0]
	v_fmac_f32_e32 v15, v3, v15
	v_div_scale_f32 v3, vcc, v51, v25, v51
	v_pk_mul_f32 v[26:27], v[26:27], v[42:43]
	v_mul_f32_e32 v42, v3, v15
	v_fma_f32 v43, -v13, v42, v3
	v_fmac_f32_e32 v42, v43, v15
	v_fma_f32 v3, -v13, v42, v3
	v_div_scale_f32 v13, s[4:5], v24, v24, v50
	v_rcp_f32_e32 v43, v13
	v_div_fmas_f32 v3, v3, v15, v42
	v_div_fixup_f32 v25, v3, v25, v51
	v_fma_f32 v3, -v13, v43, 1.0
	v_fmac_f32_e32 v43, v3, v43
	v_div_scale_f32 v3, vcc, v50, v24, v50
	v_mul_f32_e32 v15, v3, v43
	v_fma_f32 v42, -v13, v15, v3
	v_fmac_f32_e32 v15, v42, v43
	v_fma_f32 v3, -v13, v15, v3
	v_div_fmas_f32 v3, v3, v43, v15
	v_div_fixup_f32 v24, v3, v24, v50
	v_pk_mul_f32 v[24:25], v[24:25], v[26:27]
	v_pk_mul_f32 v[38:39], v[38:39], v[14:15] op_sel_hi:[1,0]
	v_cvt_pk_bf16_f32 v3, v24, v25
	global_store_dwordx2 v[40:41], v[2:3], off
	v_mov_b64_e32 v[2:3], v[156:157]
	s_nop 0
	v_mov_b64_e32 v[24:25], v[172:173]
	v_mov_b64_e32 v[26:27], v[174:175]
	v_or_b32_e32 v40, s8, v123
	v_ashrrev_i32_e32 v41, 31, v40
	v_lshl_add_u64 v[40:41], v[40:41], 1, v[4:5]
	v_lshlrev_b32_e32 v13, 16, v2
	v_and_b32_e32 v15, 0xffff0000, v2
	v_lshlrev_b32_e32 v42, 16, v3
	v_and_b32_e32 v43, 0xffff0000, v3
	v_pk_mul_f32 v[2:3], v[24:25], v[38:39]
	v_mul_f32_e32 v24, 0xbfb8aa3b, v13
	v_mul_f32_e32 v25, 0xbfb8aa3b, v15
	v_exp_f32_e32 v24, v24
	v_exp_f32_e32 v25, v25
	v_mul_f32_e32 v38, 0xbfb8aa3b, v42
	v_mul_f32_e32 v39, 0xbfb8aa3b, v43
	v_exp_f32_e32 v38, v38
	v_pk_add_f32 v[24:25], v[24:25], 1.0 op_sel_hi:[1,0]
	v_exp_f32_e32 v39, v39
	v_div_scale_f32 v44, s[4:5], v25, v25, v15
	v_div_scale_f32 v46, s[4:5], v24, v24, v13
	v_rcp_f32_e32 v47, v44
	v_rcp_f32_e32 v48, v46
	v_div_scale_f32 v45, vcc, v15, v25, v15
	v_fma_f32 v50, -v44, v47, 1.0
	v_fma_f32 v51, -v46, v48, 1.0
	v_fmac_f32_e32 v47, v50, v47
	v_div_scale_f32 v49, s[4:5], v13, v24, v13
	v_fmac_f32_e32 v48, v51, v48
	v_mul_f32_e32 v50, v45, v47
	v_mul_f32_e32 v51, v49, v48
	v_fma_f32 v52, -v44, v50, v45
	v_fma_f32 v53, -v46, v51, v49
	v_fmac_f32_e32 v50, v52, v47
	v_fmac_f32_e32 v51, v53, v48
	v_fma_f32 v44, -v44, v50, v45
	v_fma_f32 v45, -v46, v51, v49
	v_div_fmas_f32 v44, v44, v47, v50
	s_mov_b64 vcc, s[4:5]
	v_div_fixup_f32 v25, v44, v25, v15
	v_div_fmas_f32 v15, v45, v48, v51
	v_div_fixup_f32 v24, v15, v24, v13
	v_pk_mul_f32 v[2:3], v[24:25], v[2:3]
	v_pk_add_f32 v[24:25], v[38:39], 1.0 op_sel_hi:[1,0]
	v_cvt_pk_bf16_f32 v2, v2, v3
	v_div_scale_f32 v13, s[4:5], v25, v25, v43
	v_rcp_f32_e32 v15, v13
	s_nop 0
	v_fma_f32 v3, -v13, v15, 1.0
	v_pk_mul_f32 v[34:35], v[34:35], v[14:15] op_sel_hi:[1,0]
	v_fmac_f32_e32 v15, v3, v15
	v_div_scale_f32 v3, vcc, v43, v25, v43
	v_pk_mul_f32 v[26:27], v[26:27], v[34:35]
	v_mul_f32_e32 v34, v3, v15
	v_fma_f32 v35, -v13, v34, v3
	v_fmac_f32_e32 v34, v35, v15
	v_fma_f32 v3, -v13, v34, v3
	v_div_scale_f32 v13, s[4:5], v24, v24, v42
	v_rcp_f32_e32 v35, v13
	v_div_fmas_f32 v3, v3, v15, v34
	v_div_fixup_f32 v25, v3, v25, v43
	v_fma_f32 v3, -v13, v35, 1.0
	v_fmac_f32_e32 v35, v3, v35
	v_div_scale_f32 v3, vcc, v42, v24, v42
	v_mul_f32_e32 v15, v3, v35
	v_fma_f32 v34, -v13, v15, v3
	v_fmac_f32_e32 v15, v34, v35
	v_fma_f32 v3, -v13, v15, v3
	v_div_fmas_f32 v3, v3, v35, v15
	v_div_fixup_f32 v24, v3, v24, v42
	v_pk_mul_f32 v[24:25], v[24:25], v[26:27]
	v_pk_mul_f32 v[36:37], v[36:37], v[14:15] op_sel_hi:[1,0]
	v_cvt_pk_bf16_f32 v3, v24, v25
	global_store_dwordx2 v[40:41], v[2:3], off
	v_mov_b64_e32 v[2:3], v[158:159]
	s_nop 0
	v_mov_b64_e32 v[24:25], v[176:177]
	v_mov_b64_e32 v[26:27], v[178:179]
	v_pk_mul_f32 v[32:33], v[32:33], v[14:15] op_sel_hi:[1,0]
	v_or_b32_e32 v34, s8, v122
	v_ashrrev_i32_e32 v35, 31, v34
	v_lshl_add_u64 v[34:35], v[34:35], 1, v[4:5]
	v_lshlrev_b32_e32 v13, 16, v2
	v_and_b32_e32 v15, 0xffff0000, v2
	v_lshlrev_b32_e32 v40, 16, v3
	v_and_b32_e32 v41, 0xffff0000, v3
	v_mul_f32_e32 v2, 0xbfb8aa3b, v13
	v_mul_f32_e32 v3, 0xbfb8aa3b, v15
	v_exp_f32_e32 v2, v2
	v_exp_f32_e32 v3, v3
	v_mul_f32_e32 v38, 0xbfb8aa3b, v40
	v_mul_f32_e32 v39, 0xbfb8aa3b, v41
	v_exp_f32_e32 v38, v38
	v_exp_f32_e32 v39, v39
	v_pk_add_f32 v[2:3], v[2:3], 1.0 op_sel_hi:[1,0]
	v_pk_mul_f32 v[24:25], v[24:25], v[36:37]
	v_div_scale_f32 v36, s[4:5], v3, v3, v15
	v_pk_mul_f32 v[26:27], v[26:27], v[32:33]
	v_pk_add_f32 v[32:33], v[38:39], 1.0 op_sel_hi:[1,0]
	v_div_scale_f32 v38, s[4:5], v2, v2, v13
	v_rcp_f32_e32 v45, v36
	v_rcp_f32_e32 v46, v38
	v_div_scale_f32 v42, s[6:7], v33, v33, v41
	v_rcp_f32_e32 v47, v42
	v_fma_f32 v49, -v36, v45, 1.0
	v_div_scale_f32 v37, vcc, v15, v3, v15
	v_fma_f32 v50, -v38, v46, 1.0
	v_fmac_f32_e32 v45, v49, v45
	v_div_scale_f32 v39, s[4:5], v13, v2, v13
	v_fmac_f32_e32 v46, v50, v46
	v_mul_f32_e32 v49, v37, v45
	v_mul_f32_e32 v50, v39, v46
	v_fma_f32 v53, -v36, v49, v37
	v_div_scale_f32 v44, s[8:9], v32, v32, v40
	v_fma_f32 v51, -v42, v47, 1.0
	v_fma_f32 v54, -v38, v50, v39
	v_fmac_f32_e32 v49, v53, v45
	v_div_scale_f32 v43, s[6:7], v41, v33, v41
	v_rcp_f32_e32 v48, v44
	v_fmac_f32_e32 v47, v51, v47
	v_fmac_f32_e32 v50, v54, v46
	v_fma_f32 v36, -v36, v49, v37
	v_mul_f32_e32 v51, v43, v47
	v_fma_f32 v37, -v38, v50, v39
	v_div_fmas_f32 v36, v36, v45, v49
	s_mov_b64 vcc, s[4:5]
	v_fma_f32 v55, -v42, v51, v43
	v_div_fixup_f32 v3, v36, v3, v15
	v_div_fmas_f32 v15, v37, v46, v50
	v_fmac_f32_e32 v51, v55, v47
	v_div_fixup_f32 v2, v15, v2, v13
	v_fma_f32 v52, -v44, v48, 1.0
	v_fma_f32 v38, -v42, v51, v43
	s_mov_b64 vcc, s[6:7]
	v_pk_mul_f32 v[2:3], v[2:3], v[24:25]
	v_div_fmas_f32 v13, v38, v47, v51
	v_cvt_pk_bf16_f32 v2, v2, v3
	v_fmac_f32_e32 v48, v52, v48
	v_div_scale_f32 v3, vcc, v40, v32, v40
	v_div_fixup_f32 v25, v13, v33, v41
	v_mul_f32_e32 v13, v3, v48
	v_fma_f32 v15, -v44, v13, v3
	v_fmac_f32_e32 v13, v15, v48
	v_fma_f32 v3, -v44, v13, v3
	v_div_fmas_f32 v3, v3, v48, v13
	v_div_fixup_f32 v24, v3, v32, v40
	v_pk_mul_f32 v[24:25], v[24:25], v[26:27]
	v_pk_mul_f32 v[28:29], v[28:29], v[14:15] op_sel_hi:[1,0]
	v_cvt_pk_bf16_f32 v3, v24, v25
	global_store_dwordx2 v[34:35], v[2:3], off
	v_mov_b64_e32 v[2:3], v[160:161]
	s_nop 0
	v_mov_b64_e32 v[24:25], v[180:181]
	v_mov_b64_e32 v[26:27], v[182:183]
	v_pk_mul_f32 v[30:31], v[30:31], v[14:15] op_sel_hi:[1,0]
	v_or_b32_e32 v32, 64, v12
	v_ashrrev_i32_e32 v33, 31, v32
	v_lshl_add_u64 v[32:33], v[32:33], 1, v[4:5]
	v_lshlrev_b32_e32 v13, 16, v2
	v_and_b32_e32 v15, 0xffff0000, v2
	v_lshlrev_b32_e32 v36, 16, v3
	v_and_b32_e32 v37, 0xffff0000, v3
	v_mul_f32_e32 v2, 0xbfb8aa3b, v13
	v_mul_f32_e32 v3, 0xbfb8aa3b, v15
	v_exp_f32_e32 v2, v2
	v_exp_f32_e32 v3, v3
	v_mul_f32_e32 v34, 0xbfb8aa3b, v36
	v_mul_f32_e32 v35, 0xbfb8aa3b, v37
	v_exp_f32_e32 v34, v34
	v_exp_f32_e32 v35, v35
	v_pk_add_f32 v[2:3], v[2:3], 1.0 op_sel_hi:[1,0]
	v_pk_mul_f32 v[26:27], v[26:27], v[30:31]
	v_div_scale_f32 v30, s[4:5], v3, v3, v15
	v_pk_mul_f32 v[24:25], v[24:25], v[28:29]
	v_pk_add_f32 v[28:29], v[34:35], 1.0 op_sel_hi:[1,0]
	v_div_scale_f32 v34, s[4:5], v2, v2, v13
	v_rcp_f32_e32 v42, v30
	v_div_scale_f32 v38, s[6:7], v29, v29, v37
	v_rcp_f32_e32 v43, v34
	v_div_scale_f32 v40, s[8:9], v28, v28, v36
	v_rcp_f32_e32 v44, v38
	v_rcp_f32_e32 v45, v40
	v_fma_f32 v46, -v30, v42, 1.0
	v_div_scale_f32 v31, vcc, v15, v3, v15
	v_fma_f32 v47, -v34, v43, 1.0
	v_fmac_f32_e32 v42, v46, v42
	v_div_scale_f32 v35, s[4:5], v13, v2, v13
	v_fma_f32 v48, -v38, v44, 1.0
	v_fmac_f32_e32 v43, v47, v43
	v_mul_f32_e32 v46, v31, v42
	v_div_scale_f32 v39, s[6:7], v37, v29, v37
	v_fma_f32 v49, -v40, v45, 1.0
	v_fmac_f32_e32 v44, v48, v44
	v_mul_f32_e32 v47, v35, v43
	v_fma_f32 v50, -v30, v46, v31
	v_div_scale_f32 v41, s[8:9], v36, v28, v36
	v_fmac_f32_e32 v45, v49, v45
	v_mul_f32_e32 v48, v39, v44
	v_fma_f32 v51, -v34, v47, v35
	v_fmac_f32_e32 v46, v50, v42
	v_mul_f32_e32 v49, v41, v45
	v_fma_f32 v52, -v38, v48, v39
	v_fmac_f32_e32 v47, v51, v43
	v_fma_f32 v30, -v30, v46, v31
	v_fma_f32 v53, -v40, v49, v41
	v_fmac_f32_e32 v48, v52, v44
	v_fma_f32 v31, -v34, v47, v35
	v_div_fmas_f32 v30, v30, v42, v46
	s_mov_b64 vcc, s[4:5]
	v_fmac_f32_e32 v49, v53, v45
	v_fma_f32 v34, -v38, v48, v39
	v_div_fixup_f32 v3, v30, v3, v15
	v_div_fmas_f32 v15, v31, v43, v47
	s_mov_b64 vcc, s[6:7]
	v_fma_f32 v35, -v40, v49, v41
	v_div_fixup_f32 v2, v15, v2, v13
	v_div_fmas_f32 v13, v34, v44, v48
	s_mov_b64 vcc, s[8:9]
	v_pk_mul_f32 v[2:3], v[2:3], v[24:25]
	v_div_fixup_f32 v25, v13, v29, v37
	v_div_fmas_f32 v13, v35, v45, v49
	v_div_fixup_f32 v24, v13, v28, v36
	v_pk_mul_f32 v[24:25], v[24:25], v[26:27]
	v_cvt_pk_bf16_f32 v2, v2, v3
	v_cvt_pk_bf16_f32 v3, v24, v25
	global_store_dwordx2 v[32:33], v[2:3], off
	v_mov_b64_e32 v[2:3], v[162:163]
	s_nop 0
	v_mov_b64_e32 v[24:25], v[184:185]
	v_mov_b64_e32 v[26:27], v[186:187]
	v_pk_mul_f32 v[20:21], v[20:21], v[14:15] op_sel_hi:[1,0]
	v_pk_mul_f32 v[22:23], v[22:23], v[14:15] op_sel_hi:[1,0]
	v_or_b32_e32 v28, 0x50, v12
	v_ashrrev_i32_e32 v29, 31, v28
	v_lshl_add_u64 v[28:29], v[28:29], 1, v[4:5]
	v_lshlrev_b32_e32 v13, 16, v2
	v_and_b32_e32 v15, 0xffff0000, v2
	v_lshlrev_b32_e32 v32, 16, v3
	v_and_b32_e32 v33, 0xffff0000, v3
	v_mul_f32_e32 v2, 0xbfb8aa3b, v13
	v_mul_f32_e32 v3, 0xbfb8aa3b, v15
	v_exp_f32_e32 v2, v2
	v_exp_f32_e32 v3, v3
	v_mul_f32_e32 v30, 0xbfb8aa3b, v32
	v_mul_f32_e32 v31, 0xbfb8aa3b, v33
	v_exp_f32_e32 v30, v30
	v_exp_f32_e32 v31, v31
	v_pk_add_f32 v[2:3], v[2:3], 1.0 op_sel_hi:[1,0]
	v_pk_mul_f32 v[22:23], v[26:27], v[22:23]
	v_div_scale_f32 v26, s[4:5], v3, v3, v15
	v_pk_mul_f32 v[20:21], v[24:25], v[20:21]
	v_pk_add_f32 v[24:25], v[30:31], 1.0 op_sel_hi:[1,0]
	v_div_scale_f32 v30, s[4:5], v2, v2, v13
	v_rcp_f32_e32 v38, v26
	v_div_scale_f32 v34, s[6:7], v25, v25, v33
	v_rcp_f32_e32 v39, v30
	v_div_scale_f32 v36, s[8:9], v24, v24, v32
	v_rcp_f32_e32 v40, v34
	v_rcp_f32_e32 v41, v36
	v_fma_f32 v42, -v26, v38, 1.0
	v_div_scale_f32 v27, vcc, v15, v3, v15
	v_fma_f32 v43, -v30, v39, 1.0
	v_fmac_f32_e32 v38, v42, v38
	v_div_scale_f32 v31, s[4:5], v13, v2, v13
	v_fma_f32 v44, -v34, v40, 1.0
	v_fmac_f32_e32 v39, v43, v39
	v_mul_f32_e32 v42, v27, v38
	v_div_scale_f32 v35, s[6:7], v33, v25, v33
	v_fma_f32 v45, -v36, v41, 1.0
	v_fmac_f32_e32 v40, v44, v40
	v_mul_f32_e32 v43, v31, v39
	v_fma_f32 v46, -v26, v42, v27
	v_div_scale_f32 v37, s[8:9], v32, v24, v32
	v_fmac_f32_e32 v41, v45, v41
	v_mul_f32_e32 v44, v35, v40
	v_fma_f32 v47, -v30, v43, v31
	v_fmac_f32_e32 v42, v46, v38
	v_mul_f32_e32 v45, v37, v41
	v_fma_f32 v48, -v34, v44, v35
	v_fmac_f32_e32 v43, v47, v39
	v_fma_f32 v26, -v26, v42, v27
	v_fma_f32 v49, -v36, v45, v37
	v_fmac_f32_e32 v44, v48, v40
	v_fma_f32 v27, -v30, v43, v31
	v_div_fmas_f32 v26, v26, v38, v42
	s_mov_b64 vcc, s[4:5]
	v_fmac_f32_e32 v45, v49, v41
	v_fma_f32 v30, -v34, v44, v35
	v_div_fixup_f32 v3, v26, v3, v15
	v_div_fmas_f32 v15, v27, v39, v43
	s_mov_b64 vcc, s[6:7]
	v_fma_f32 v31, -v36, v45, v37
	v_div_fixup_f32 v2, v15, v2, v13
	v_div_fmas_f32 v13, v30, v40, v44
	s_mov_b64 vcc, s[8:9]
	v_pk_mul_f32 v[2:3], v[2:3], v[20:21]
	v_div_fixup_f32 v21, v13, v25, v33
	v_div_fmas_f32 v13, v31, v41, v45
	v_div_fixup_f32 v20, v13, v24, v32
	v_pk_mul_f32 v[20:21], v[20:21], v[22:23]
	v_cvt_pk_bf16_f32 v2, v2, v3
	v_cvt_pk_bf16_f32 v3, v20, v21
	global_store_dwordx2 v[28:29], v[2:3], off
	v_mov_b64_e32 v[2:3], v[164:165]
	s_nop 0
	v_mov_b64_e32 v[20:21], v[188:189]
	v_mov_b64_e32 v[22:23], v[190:191]
	v_pk_mul_f32 v[18:19], v[18:19], v[14:15] op_sel_hi:[1,0]
	v_pk_mul_f32 v[16:17], v[16:17], v[14:15] op_sel_hi:[1,0]
	v_or_b32_e32 v24, 0x60, v12
	v_ashrrev_i32_e32 v25, 31, v24
	v_lshl_add_u64 v[24:25], v[24:25], 1, v[4:5]
	v_or_b32_e32 v12, 0x70, v12
	v_lshlrev_b32_e32 v13, 16, v2
	v_and_b32_e32 v15, 0xffff0000, v2
	v_lshlrev_b32_e32 v28, 16, v3
	v_and_b32_e32 v29, 0xffff0000, v3
	v_mul_f32_e32 v2, 0xbfb8aa3b, v13
	v_mul_f32_e32 v3, 0xbfb8aa3b, v15
	v_exp_f32_e32 v2, v2
	v_exp_f32_e32 v3, v3
	v_mul_f32_e32 v26, 0xbfb8aa3b, v28
	v_mul_f32_e32 v27, 0xbfb8aa3b, v29
	v_exp_f32_e32 v26, v26
	v_exp_f32_e32 v27, v27
	v_pk_add_f32 v[2:3], v[2:3], 1.0 op_sel_hi:[1,0]
	v_pk_mul_f32 v[16:17], v[22:23], v[16:17]
	v_div_scale_f32 v22, s[4:5], v3, v3, v15
	v_pk_mul_f32 v[18:19], v[20:21], v[18:19]
	v_pk_add_f32 v[20:21], v[26:27], 1.0 op_sel_hi:[1,0]
	v_div_scale_f32 v26, s[4:5], v2, v2, v13
	v_rcp_f32_e32 v34, v22
	v_div_scale_f32 v30, s[6:7], v21, v21, v29
	v_rcp_f32_e32 v35, v26
	v_div_scale_f32 v32, s[8:9], v20, v20, v28
	v_rcp_f32_e32 v36, v30
	v_rcp_f32_e32 v37, v32
	v_fma_f32 v38, -v22, v34, 1.0
	v_div_scale_f32 v23, vcc, v15, v3, v15
	v_fma_f32 v39, -v26, v35, 1.0
	v_fmac_f32_e32 v34, v38, v34
	v_div_scale_f32 v27, s[4:5], v13, v2, v13
	v_fma_f32 v40, -v30, v36, 1.0
	v_fmac_f32_e32 v35, v39, v35
	v_mul_f32_e32 v38, v23, v34
	v_div_scale_f32 v31, s[6:7], v29, v21, v29
	v_fma_f32 v41, -v32, v37, 1.0
	v_fmac_f32_e32 v36, v40, v36
	v_mul_f32_e32 v39, v27, v35
	v_fma_f32 v42, -v22, v38, v23
	v_div_scale_f32 v33, s[8:9], v28, v20, v28
	v_fmac_f32_e32 v37, v41, v37
	v_mul_f32_e32 v40, v31, v36
	v_fma_f32 v43, -v26, v39, v27
	v_fmac_f32_e32 v38, v42, v34
	v_mul_f32_e32 v41, v33, v37
	v_fma_f32 v44, -v30, v40, v31
	v_fmac_f32_e32 v39, v43, v35
	v_fma_f32 v22, -v22, v38, v23
	v_fma_f32 v45, -v32, v41, v33
	v_fmac_f32_e32 v40, v44, v36
	v_fma_f32 v23, -v26, v39, v27
	v_div_fmas_f32 v22, v22, v34, v38
	s_mov_b64 vcc, s[4:5]
	v_fmac_f32_e32 v41, v45, v37
	v_fma_f32 v26, -v30, v40, v31
	v_div_fixup_f32 v3, v22, v3, v15
	v_div_fmas_f32 v15, v23, v35, v39
	s_mov_b64 vcc, s[6:7]
	v_fma_f32 v27, -v32, v41, v33
	v_div_fixup_f32 v2, v15, v2, v13
	v_div_fmas_f32 v13, v26, v36, v40
	s_mov_b64 vcc, s[8:9]
	v_pk_mul_f32 v[2:3], v[2:3], v[18:19]
	v_div_fixup_f32 v19, v13, v21, v29
	v_div_fmas_f32 v13, v27, v37, v41
	v_div_fixup_f32 v18, v13, v20, v28
	v_pk_mul_f32 v[16:17], v[18:19], v[16:17]
	v_cvt_pk_bf16_f32 v2, v2, v3
	v_cvt_pk_bf16_f32 v3, v16, v17
	global_store_dwordx2 v[24:25], v[2:3], off
	v_mov_b64_e32 v[10:11], v[166:167]
	s_nop 0
	v_mov_b64_e32 v[0:1], v[192:193]
	v_mov_b64_e32 v[2:3], v[194:195]
	v_pk_mul_f32 v[6:7], v[6:7], v[14:15] op_sel_hi:[1,0]
	v_pk_mul_f32 v[8:9], v[8:9], v[14:15] op_sel_hi:[1,0]
	v_ashrrev_i32_e32 v13, 31, v12
	v_lshl_add_u64 v[4:5], v[12:13], 1, v[4:5]
	v_lshlrev_b32_e32 v14, 16, v10
	v_and_b32_e32 v15, 0xffff0000, v10
	v_lshlrev_b32_e32 v16, 16, v11
	v_and_b32_e32 v17, 0xffff0000, v11
	v_mul_f32_e32 v10, 0xbfb8aa3b, v14
	v_mul_f32_e32 v11, 0xbfb8aa3b, v15
	v_exp_f32_e32 v10, v10
	v_exp_f32_e32 v11, v11
	v_mul_f32_e32 v12, 0xbfb8aa3b, v16
	v_mul_f32_e32 v13, 0xbfb8aa3b, v17
	v_exp_f32_e32 v12, v12
	v_exp_f32_e32 v13, v13
	v_pk_mul_f32 v[0:1], v[0:1], v[6:7]
	v_pk_add_f32 v[6:7], v[10:11], 1.0 op_sel_hi:[1,0]
	v_pk_mul_f32 v[2:3], v[2:3], v[8:9]
	v_div_scale_f32 v10, s[4:5], v7, v7, v15
	v_pk_add_f32 v[8:9], v[12:13], 1.0 op_sel_hi:[1,0]
	v_div_scale_f32 v12, s[4:5], v6, v6, v14
	v_rcp_f32_e32 v22, v10
	v_div_scale_f32 v18, s[6:7], v9, v9, v17
	v_rcp_f32_e32 v23, v12
	v_div_scale_f32 v20, s[8:9], v8, v8, v16
	v_rcp_f32_e32 v24, v18
	v_rcp_f32_e32 v25, v20
	v_fma_f32 v26, -v10, v22, 1.0
	v_div_scale_f32 v11, vcc, v15, v7, v15
	v_fma_f32 v27, -v12, v23, 1.0
	v_fmac_f32_e32 v22, v26, v22
	v_div_scale_f32 v13, s[4:5], v14, v6, v14
	v_fma_f32 v28, -v18, v24, 1.0
	v_fmac_f32_e32 v23, v27, v23
	v_mul_f32_e32 v26, v11, v22
	v_div_scale_f32 v19, s[6:7], v17, v9, v17
	v_fma_f32 v29, -v20, v25, 1.0
	v_fmac_f32_e32 v24, v28, v24
	v_mul_f32_e32 v27, v13, v23
	v_fma_f32 v30, -v10, v26, v11
	v_div_scale_f32 v21, s[8:9], v16, v8, v16
	v_fmac_f32_e32 v25, v29, v25
	v_mul_f32_e32 v28, v19, v24
	v_fma_f32 v31, -v12, v27, v13
	v_fmac_f32_e32 v26, v30, v22
	v_mul_f32_e32 v29, v21, v25
	v_fma_f32 v32, -v18, v28, v19
	v_fmac_f32_e32 v27, v31, v23
	v_fma_f32 v10, -v10, v26, v11
	v_fma_f32 v33, -v20, v29, v21
	v_fmac_f32_e32 v28, v32, v24
	v_fma_f32 v11, -v12, v27, v13
	v_div_fmas_f32 v10, v10, v22, v26
	s_mov_b64 vcc, s[4:5]
	v_fmac_f32_e32 v29, v33, v25
	v_fma_f32 v12, -v18, v28, v19
	v_div_fixup_f32 v7, v10, v7, v15
	v_div_fmas_f32 v10, v11, v23, v27
	s_mov_b64 vcc, s[6:7]
	v_fma_f32 v13, -v20, v29, v21
	v_div_fixup_f32 v6, v10, v6, v14
	v_div_fmas_f32 v10, v12, v24, v28
	s_mov_b64 vcc, s[8:9]
	v_pk_mul_f32 v[0:1], v[6:7], v[0:1]
	v_div_fmas_f32 v6, v13, v25, v29
	v_div_fixup_f32 v7, v10, v9, v17
	v_div_fixup_f32 v6, v6, v8, v16
	v_pk_mul_f32 v[2:3], v[6:7], v[2:3]
	v_cvt_pk_bf16_f32 v0, v0, v1
	v_cvt_pk_bf16_f32 v1, v2, v3
	s_mov_b64 s[4:5], 0
	global_store_dwordx2 v[4:5], v[0:1], off
